# cooperative-groups grid sync after the prologue replaced by the counter+flag seam barrier
# speedup vs baseline: 1.0234x; 1.0062x over previous
.LBB0_86:
.LBB0_98:
	s_mov_b32 s76, 1
.LBB0_99:
	s_cmp_ge_i32 s76, s87
	v_readlane_b32 s2, v252, 0
	s_cbranch_scc1 .LBB0_797
	s_load_dwordx8 s[88:95], s[72:73], 0xc0
	s_max_i32 s0, s86, 0
	v_writelane_b32 v252, s0, 61
	s_and_b32 s0, s44, 0xffffffc0
	v_writelane_b32 v252, s0, 62
	s_waitcnt lgkmcnt(0)
	s_add_u32 s0, s94, 0x1000
	v_writelane_b32 v252, s0, 63
	s_addc_u32 s0, s95, 0
	s_add_u32 s94, s72, 0xe8
	v_writelane_b32 v253, s0, 0
	s_addc_u32 s95, s73, 0
	s_lshl_b32 s0, s2, 3
	s_add_i32 s50, s33, s0
	s_cmpk_lt_i32 s50, 0x800
	s_cselect_b64 s[0:1], -1, 0
	s_lshl_b32 s78, s50, 3
	v_writelane_b32 v253, s0, 1
	s_add_i32 s80, s78, 0xffffe000
	s_mov_b32 s81, 0
	v_writelane_b32 v253, s1, 2
	s_lshr_b32 s0, s80, 11
	s_add_i32 s12, s0, 1
	s_lshl_b64 s[0:1], s[80:81], 13
	s_add_u32 s13, s18, s0
	s_addc_u32 s14, s19, s1
	s_ashr_i32 s79, s78, 31
	s_lshl_b64 s[6:7], s[78:79], 13
	s_add_u32 s15, s16, s6
	s_addc_u32 s34, s17, s7
	s_cmpk_lt_i32 s2, 0xc0
	s_cselect_b64 s[0:1], -1, 0
	v_writelane_b32 v253, s0, 3
	v_readlane_b32 s16, v252, 17
	v_readlane_b32 s30, v252, 31
	v_writelane_b32 v253, s1, 4
	s_lshl_b32 s0, s2, 9
	v_writelane_b32 v253, s0, 5
	s_mul_i32 s0, s33, 0x4100
	s_add_i32 s0, s0, 0
	s_cmpk_lt_i32 s50, 0x6e40
	v_writelane_b32 v253, s0, 6
	s_cselect_b64 s[0:1], -1, 0
	v_writelane_b32 v253, s0, 7
	v_readlane_b32 s31, v252, 32
	v_readlane_b32 s24, v252, 25
	v_writelane_b32 v253, s1, 8
	s_mul_hi_i32 s0, s50, 0x4a4dc96f
	s_lshr_b32 s1, s0, 31
	s_ashr_i32 s0, s0, 12
	s_add_i32 s0, s0, s1
	s_mul_i32 s1, s0, 0x3720
	s_sub_i32 s9, s50, s1
	s_cmpk_gt_i32 s9, 0x121f
	s_cselect_b64 s[2:3], -1, 0
	s_cmpk_lt_i32 s9, 0x1220
	v_writelane_b32 v253, s2, 9
	s_cselect_b64 s[4:5], -1, 0
	s_cmpk_lt_u32 s9, 0x2c20
	v_writelane_b32 v253, s3, 10
	s_cselect_b64 s[2:3], -1, 0
	s_ashr_i32 s1, s0, 31
	s_mul_i32 s8, s0, 0x2c00000
	s_add_u32 s35, s30, s8
	s_mul_hi_i32 s8, s0, 0x2c00000
	s_addc_u32 s36, s31, s8
	s_mul_i32 s8, s0, 0x5800000
	v_readlane_b32 s25, v252, 26
	s_add_u32 s37, s24, s8
	s_mul_hi_i32 s8, s0, 0x5800000
	v_readlane_b32 s18, v252, 19
	s_addc_u32 s38, s25, s8
	s_add_i32 s39, s9, 0xede0
	s_lshl_b64 s[10:11], s[0:1], 24
	v_readlane_b32 s19, v252, 20
	s_add_u32 s40, s18, s10
	v_readlane_b32 s52, v252, 1
	s_addc_u32 s11, s19, s11
	s_mul_hi_i32 s1, s0, 0x2440000
	s_mul_i32 s0, s0, 0x2440000
	v_readlane_b32 s56, v252, 5
	v_readlane_b32 s29, v252, 30
	v_readlane_b32 s57, v252, 6
	s_add_u32 s41, s56, s0
	v_readlane_b32 s29, v252, 0
	s_addc_u32 s42, s57, s1
	s_cmpk_lt_i32 s29, 0x400
	s_cselect_b64 s[0:1], -1, 0
	v_writelane_b32 v253, s0, 11
	s_lshl_b32 s16, s33, 5
	v_readlane_b32 s17, v252, 18
	v_writelane_b32 v253, s1, 12
	s_lshl_b32 s0, s33, 3
	v_writelane_b32 v253, s0, 13
	s_add_u32 s0, s92, 0x8000000
	v_writelane_b32 v253, s0, 14
	s_addc_u32 s0, s93, 0
	v_writelane_b32 v253, s0, 15
	s_add_u32 s0, s92, 0x9000000
	v_writelane_b32 v253, s0, 16
	s_addc_u32 s0, s93, 0
	s_lshr_b32 s17, s44, 8
	v_writelane_b32 v253, s0, 17
	s_lshl_b32 s1, s17, 6
	s_bfe_u32 s0, s44, 0x20006
	v_writelane_b32 v253, s1, 18
	s_lshl_b32 s1, s17, 13
	v_writelane_b32 v253, s1, 19
	s_lshl_b32 s1, s0, 5
	s_lshl_b32 s49, s33, 10
	v_writelane_b32 v253, s1, 20
	s_lshl_b32 s1, s0, 12
	s_cmpk_lt_i32 s29, 0x4c0
	v_writelane_b32 v253, s1, 21
	s_cselect_b64 s[18:19], -1, 0
	v_writelane_b32 v253, s18, 22
	s_ashr_i32 s1, s29, 31
	v_readlane_b32 s22, v252, 23
	v_writelane_b32 v253, s19, 23
	v_writelane_b32 v253, s1, 24
	s_lshr_b32 s1, s1, 29
	s_add_i32 s1, s29, s1
	s_ashr_i32 s43, s1, 3
	s_and_b32 s1, s1, -8
	s_sub_i32 s1, s29, s1
	s_lshl_b32 s8, s1, 6
	s_cmp_lt_i32 s1, 0
	s_mul_i32 s10, s1, 0x41
	s_cselect_b32 s45, s10, s8
	s_movk_i32 s8, 0x99
	s_cselect_b32 s8, s8, 0x98
	s_mul_i32 s8, s8, s1
	s_movk_i32 s10, 0x161
	s_cselect_b32 s10, s10, 0x160
	s_add_i32 s8, s8, s43
	s_mul_hi_i32 s46, s8, 0x6bca1af3
	s_lshr_b32 s47, s46, 31
	s_ashr_i32 s46, s46, 6
	s_add_i32 s46, s46, s47
	s_mul_i32 s47, s46, 0x98
	s_sub_i32 s8, s8, s47
	s_bfe_u32 s47, s8, 0x3001c
	s_add_i32 s47, s8, s47
	s_and_b32 s48, s47, 0xfff8
	s_sub_i32 s8, s8, s48
	s_mul_i32 s1, s10, s1
	s_lshl_b32 s10, s46, 3
	s_sext_i32_i16 s46, s47
	s_sext_i32_i16 s8, s8
	s_add_i32 s22, s10, s8
	s_ashr_i32 s8, s46, 3
	v_writelane_b32 v253, s8, 25
	s_lshr_b32 s8, s46, 3
	s_cmp_eq_u32 s17, 1
	s_cselect_b64 s[18:19], -1, 0
	v_writelane_b32 v253, s18, 26
	s_cmp_eq_u32 s0, 0
	v_readlane_b32 s60, v252, 9
	v_writelane_b32 v253, s19, 27
	s_cselect_b64 s[18:19], -1, 0
	v_writelane_b32 v253, s18, 28
	s_cmpk_lt_u32 s44, 0x100
	v_readlane_b32 s61, v252, 10
	v_writelane_b32 v253, s19, 29
	s_cselect_b64 s[18:19], -1, 0
	v_writelane_b32 v253, s18, 30
	s_cmpk_gt_u32 s44, 0xff
	v_readlane_b32 s62, v252, 11
	v_writelane_b32 v253, s19, 31
	s_cselect_b64 s[18:19], -1, 0
	v_writelane_b32 v253, s18, 32
	s_and_b32 s0, s16, 0x60
	v_readlane_b32 s63, v252, 12
	v_writelane_b32 v253, s19, 33
	v_writelane_b32 v253, s0, 34
	s_lshl_b32 s0, s0, 7
	v_readlane_b32 s64, v252, 13
	v_readlane_b32 s65, v252, 14
	v_readlane_b32 s66, v252, 15
	v_readlane_b32 s67, v252, 16
	s_cmpk_lt_i32 s29, 0x200
	v_readlane_b32 s60, v252, 41
	v_writelane_b32 v253, s0, 35
	s_cselect_b64 s[18:19], -1, 0
	v_readlane_b32 s62, v252, 43
	v_writelane_b32 v253, s18, 36
	v_readlane_b32 s63, v252, 44
	s_add_u32 s0, s62, 0xfc000000
	v_writelane_b32 v253, s19, 37
	v_writelane_b32 v253, s0, 38
	s_addc_u32 s0, s63, -1
	s_cmpk_lt_i32 s29, 0xb00
	s_cselect_b64 s[18:19], -1, 0
	s_add_i32 s1, s1, s43
	v_writelane_b32 v253, s0, 39
	s_mul_hi_i32 s0, s1, 0x2e8ba2e9
	s_lshr_b32 s10, s0, 31
	s_ashr_i32 s0, s0, 6
	s_add_i32 s0, s0, s10
	s_mul_i32 s10, s0, 0x160
	s_sub_i32 s1, s1, s10
	s_bfe_u32 s10, s1, 0x3001c
	v_writelane_b32 v253, s18, 40
	s_add_i32 s10, s1, s10
	s_lshl_b32 s0, s0, 3
	v_writelane_b32 v253, s19, 41
	s_and_b32 s18, s10, 0xfff8
	s_sub_i32 s1, s1, s18
	s_sext_i32_i16 s10, s10
	s_sext_i32_i16 s1, s1
	s_add_i32 s24, s0, s1
	s_ashr_i32 s0, s10, 3
	v_writelane_b32 v253, s0, 42
	s_lshl_b32 s1, s17, 11
	s_lshr_b32 s10, s10, 3
	v_writelane_b32 v253, s17, 43
	s_add_i32 s17, s1, 0x1000
	s_cmpk_lt_u32 s44, 0x300
	s_cselect_b64 s[18:19], -1, 0
	v_writelane_b32 v253, s18, 44
	s_lshl_b32 s0, s33, 9
	s_and_b32 s0, s0, 0xfffff800
	v_writelane_b32 v253, s19, 45
	v_writelane_b32 v253, s0, 46
	s_addk_i32 s0, 0xfc00
	v_writelane_b32 v253, s0, 47
	s_add_i32 s0, 0, 0x20000
	v_writelane_b32 v253, s1, 48
	s_add_i32 s1, s0, s1
	v_writelane_b32 v253, s1, 49
	s_addk_i32 s1, 0x400
	v_writelane_b32 v253, s1, 50
	v_writelane_b32 v253, s17, 51
	v_writelane_b32 v253, s0, 52
	s_add_i32 s0, s0, s17
	v_readlane_b32 s26, v252, 27
	v_readlane_b32 s27, v252, 28
	v_writelane_b32 v253, s0, 53
	s_addk_i32 s0, 0x400
	v_readlane_b32 s20, v252, 21
	v_readlane_b32 s21, v252, 22
	v_writelane_b32 v253, s0, 54
	s_lshl_b64 s[26:27], s[78:79], 12
	s_lshl_b64 s[0:1], s[78:79], 11
	s_cmp_lg_u64 s[20:21], 0
	s_cselect_b64 s[18:19], -1, 0
	v_writelane_b32 v253, s18, 55
	s_add_u32 s6, s92, s6
	v_readlane_b32 s23, v252, 24
	v_writelane_b32 v253, s19, 56
	v_writelane_b32 v253, s6, 57
	s_addc_u32 s6, s93, s7
	s_cmp_lg_u64 s[88:89], 0
	v_writelane_b32 v253, s6, 58
	s_cselect_b64 s[6:7], -1, 0
	v_writelane_b32 v253, s6, 59
	s_cmpk_lt_i32 s50, 0x400
	s_cselect_b32 s12, 0, s12
	v_writelane_b32 v253, s7, 60
	v_writelane_b32 v253, s50, 61
	s_cselect_b32 s7, s34, s14
	s_cselect_b32 s6, s15, s13
	v_writelane_b32 v253, s6, 62
	s_mul_i32 s13, s12, 0xc000
	s_mov_b32 s19, s81
	v_writelane_b32 v253, s7, 63
	s_cselect_b32 s7, s79, 0
	v_writelane_b32 v254, s78, 0
	s_cselect_b32 s6, s78, s78
	v_readlane_b32 s53, v252, 2
	v_writelane_b32 v254, s79, 1
	v_writelane_b32 v254, s12, 2
	s_add_i32 s12, s12, 5
	v_writelane_b32 v254, s13, 3
	s_add_i32 s13, s13, 0x3c000
	s_cmpk_lt_i32 s29, 0x800
	v_writelane_b32 v254, s13, 4
	s_cselect_b64 s[14:15], -1, 0
	v_writelane_b32 v254, s14, 5
	s_lshl_b64 s[6:7], s[6:7], 12
	s_cmpk_lt_i32 s9, 0x1620
	v_writelane_b32 v254, s15, 6
	v_writelane_b32 v254, s6, 7
	v_readlane_b32 s28, v252, 29
	v_readlane_b32 s54, v252, 3
	v_writelane_b32 v254, s7, 8
	s_cselect_b64 s[6:7], -1, 0
	s_and_b64 s[4:5], s[4:5], exec
	s_cselect_b32 s4, s42, s11
	s_movk_i32 s11, 0x1220
	s_cselect_b32 s5, s41, s40
	s_cselect_b32 s11, s11, 0x800
	s_cselect_b32 s13, s9, s39
	s_and_b64 s[2:3], s[2:3], exec
	s_mov_b32 s2, 0xe9e0
	s_cselect_b32 s2, s2, 0xd3e0
	s_movk_i32 s3, 0x2c00
	s_cselect_b32 s14, s37, s35
	s_cselect_b32 s15, s38, s36
	s_cselect_b32 s18, s3, 0x800
	s_add_i32 s9, s9, s2
	s_and_b64 s[2:3], s[6:7], exec
	s_cselect_b32 s6, s13, s9
	s_cselect_b32 s17, s11, s18
	s_cselect_b32 s7, s4, s15
	s_cselect_b32 s9, s5, s14
	s_add_i32 s2, s45, s43
	s_ashr_i32 s3, s2, 31
	s_lshr_b32 s3, s3, 26
	s_add_i32 s3, s2, s3
	s_and_b32 s13, s3, 0xffc0
	s_sub_i32 s2, s2, s13
	s_bfe_i32 s13, s2, 0x80000
	s_bfe_u32 s13, s13, 0x3000c
	s_add_i32 s13, s2, s13
	s_and_b32 s14, s13, 0xf8
	s_sub_i32 s2, s2, s14
	s_ashr_i32 s3, s3, 6
	s_lshl_b32 s3, s3, 3
	s_sext_i32_i8 s2, s2
	s_add_i32 s2, s3, s2
	v_writelane_b32 v254, s2, 9
	s_bfe_i64 s[2:3], s[8:9], 0x100000
	s_lshl_b64 s[2:3], s[2:3], 20
	v_writelane_b32 v254, s2, 10
	s_lshr_b32 s11, s11, 5
	s_ashr_i32 s23, s22, 31
	v_writelane_b32 v254, s3, 11
	s_bfe_i32 s2, s13, 0x80000
	s_sext_i32_i16 s8, s2
	s_bfe_i64 s[2:3], s[10:11], 0x100000
	s_lshl_b64 s[2:3], s[2:3], 20
	v_writelane_b32 v254, s2, 12
	s_lshr_b32 s10, s17, 6
	v_cvt_f32_ubyte0_e32 v1, s10
	v_writelane_b32 v254, s3, 13
	s_ashr_i32 s2, s8, 3
	v_writelane_b32 v254, s2, 14
	s_lshr_b32 s2, s8, 3
	s_bfe_i64 s[2:3], s[2:3], 0x100000
	v_writelane_b32 v254, s2, 15
	s_sext_i32_i16 s8, s6
	v_cvt_f32_i32_e32 v0, s8
	v_writelane_b32 v254, s3, 16
	s_xor_b32 s2, s8, s10
	s_ashr_i32 s2, s2, 30
	s_or_b32 s13, s2, 1
	v_writelane_b32 v254, s17, 17
	s_mov_b32 s2, s22
	s_waitcnt vmcnt(15)
	v_rcp_iflag_f32_e32 v2, v1
	v_writelane_b32 v254, s2, 18
	s_ashr_i32 s25, s24, 31
	s_lshl_b32 s14, s17, 4
	v_writelane_b32 v254, s3, 19
	s_lshl_b64 s[2:3], s[22:23], 20
	v_writelane_b32 v254, s2, 20
	v_mul_f32_e32 v2, v0, v2
	v_trunc_f32_e32 v2, v2
	v_writelane_b32 v254, s3, 21
	s_mov_b32 s2, s24
	v_writelane_b32 v254, s2, 22
	v_fma_f32 v3, -v2, v1, v0
	s_lshl_b32 s18, s17, 3
	v_writelane_b32 v254, s3, 23
	s_lshl_b64 s[2:3], s[24:25], 20
	v_writelane_b32 v254, s2, 24
	s_mov_b32 s15, s81
	s_mov_b32 s17, s81
	v_writelane_b32 v254, s3, 25
	v_cmp_ge_f32_e64 s[2:3], |v3|, |v1|
	v_cvt_i32_f32_e32 v1, v2
	s_and_b64 s[2:3], s[2:3], exec
	s_cselect_b32 s2, s13, 0
	v_readlane_b32 s55, v252, 4
	v_readfirstlane_b32 s3, v1
	s_add_i32 s2, s3, s2
	s_mul_i32 s3, s2, s10
	s_sext_i32_i16 s2, s2
	s_sub_i32 s3, s6, s3
	s_sext_i32_i16 s3, s3
	s_lshl_b32 s2, s2, 6
	v_cvt_f32_ubyte0_e32 v1, s11
	v_writelane_b32 v254, s2, 26
	s_lshl_b32 s2, s3, 6
	v_rcp_iflag_f32_e32 v2, v1
	s_ashr_i32 s3, s2, 31
	s_lshl_b64 s[2:3], s[2:3], 2
	s_add_u32 s2, s9, s2
	s_addc_u32 s3, s7, s3
	v_mul_f32_e32 v2, v0, v2
	v_writelane_b32 v254, s2, 27
	v_trunc_f32_e32 v2, v2
	v_fma_f32 v0, -v2, v1, v0
	v_writelane_b32 v254, s3, 28
	s_ashr_i32 s2, s8, 30
	s_or_b32 s7, s2, 1
	v_cmp_ge_f32_e64 s[2:3], |v0|, v1
	v_cvt_i32_f32_e32 v0, v2
	s_and_b64 s[2:3], s[2:3], exec
	s_cselect_b32 s2, s7, 0
	v_readlane_b32 s58, v252, 7
	v_readfirstlane_b32 s3, v0
	s_add_i32 s2, s3, s2
	s_mul_i32 s3, s2, s11
	s_sub_i32 s3, s6, s3
	s_sext_i32_i16 s2, s2
	s_sext_i32_i16 s3, s3
	s_lshl_b32 s2, s2, 6
	v_writelane_b32 v254, s2, 29
	s_lshl_b32 s2, s3, 5
	s_ashr_i32 s3, s2, 31
	s_lshl_b64 s[2:3], s[2:3], 2
	s_add_u32 s2, s5, s2
	s_addc_u32 s3, s4, s3
	v_writelane_b32 v254, s2, 30
	v_readlane_b32 s59, v252, 8
	v_readlane_b32 s61, v252, 42
	v_writelane_b32 v254, s3, 31
	s_mul_hi_u32 s2, s12, 0xc000
	v_writelane_b32 v254, s2, 32
	v_writelane_b32 v254, s14, 33
	s_lshl_b32 s2, s33, 8
	s_add_i32 s2, s2, 0
	v_writelane_b32 v254, s15, 34
	v_writelane_b32 v254, s18, 35
	s_mulk_i32 s33, 0x2020
	v_readlane_b32 s64, v252, 45
	v_writelane_b32 v254, s19, 36
	v_writelane_b32 v254, s2, 37
	s_add_u32 s2, s52, 0x174000
	s_addc_u32 s3, s53, 0
	v_writelane_b32 v254, s2, 38
	v_readlane_b32 s65, v252, 46
	v_readlane_b32 s66, v252, 47
	v_writelane_b32 v254, s3, 39
	s_add_i32 s2, s33, 0
	v_writelane_b32 v254, s2, 40
	s_lshl_b32 s2, s29, 4
	v_writelane_b32 v254, s2, 41
	s_lshl_b32 s2, s29, 8
	v_writelane_b32 v254, s2, 42
	s_add_u32 s2, s26, 0xff01000
	v_writelane_b32 v254, s2, 43
	v_writelane_b32 v254, s26, 44
	s_addc_u32 s2, s27, 0
	s_lshl_b64 s[0:1], s[0:1], 1
	v_writelane_b32 v254, s27, 45
	v_writelane_b32 v254, s2, 46
	v_writelane_b32 v254, s0, 47
	s_mov_b32 s26, s76
	s_mov_b64 s[76:77], s[16:17]
	v_writelane_b32 v254, s1, 48
	s_add_i32 s0, 0, 0x23fc0
	v_writelane_b32 v254, s0, 49
	v_readlane_b32 s67, v252, 48
	v_readlane_b32 s68, v252, 49
	v_readlane_b32 s69, v252, 50
	v_readlane_b32 s70, v252, 51
	v_readlane_b32 s71, v252, 52
	v_readlane_b32 s72, v252, 53
	v_readlane_b32 s73, v252, 54
	v_readlane_b32 s74, v252, 55
	v_readlane_b32 s75, v252, 56
	s_mov_b32 s96, 0x24115d9a
	v_mbcnt_lo_u32_b32 v0, -1, 0
	v_writelane_b32 v252, s76, 59
	v_writelane_b32 v254, s94, 50
	v_mov_b32_e32 v1, 0
	v_mov_b32_e32 v218, 0x3727c5ac
	v_mov_b32_e32 v219, 0x260
	v_mov_b32_e32 v220, 1
	s_mov_b32 s97, 0x3fe7ff22
	v_mov_b32_e32 v221, 0x16000
	v_mov_b64_e32 v[198:199], 0xaff
	v_mov_b32_e32 v222, 0x2c00
	v_mbcnt_hi_u32_b32 v223, -1, v0
	v_mov_b32_e32 v224, 0x400
	v_mov_b64_e32 v[200:201], 0x200
	v_mov_b64_e32 v[202:203], 0x1ff
	v_mov_b32_e32 v225, 0x80
	v_mov_b32_e32 v226, 0xf149f2ca
	v_mov_b64_e32 v[204:205], 0x4bf
	v_mov_b64_e32 v[206:207], 0x4c0
	v_mov_b32_e32 v227, 0xfffffb00
	v_mov_b32_e32 v228, 0xffffff00
	v_mov_b32_e32 v229, 0x1000
	v_mov_b32_e32 v230, 0x2000
	v_mov_b32_e32 v231, 0x3000
	v_mov_b32_e32 v232, 0x9000
	v_mov_b32_e32 v233, 0xa000
	v_mov_b32_e32 v234, 0xb000
	s_movk_i32 s59, 0x100
	s_mov_b32 s50, 0xc000
	s_movk_i32 s20, 0x2000
	s_mov_b32 s33, 0x10000
	s_mov_b32 s28, 0xb000
	s_mov_b32 s46, 0x18000
	s_mov_b32 s47, 0x8000
	s_mov_b32 s30, 0xf800000
	s_movk_i32 s31, 0x88
	s_movk_i32 s53, 0x48
	s_movk_i32 s55, 0x7fff
	s_mov_b32 s82, 0x40000
	s_mov_b32 s83, 0x48000
	s_mov_b32 s54, 0x50000
	s_mov_b32 s88, 0x58000
	s_mov_b32 s48, 0x80000
	s_mov_b32 s51, 0x88000
	s_mov_b32 s52, 0x90000
	s_mov_b32 s90, 0x98000
	s_mov_b32 s91, 0xc0000
	s_mov_b32 s84, 0xc8000
	s_mov_b32 s85, 0x7060302
	s_movk_i32 s89, 0xfeff
	s_movk_i32 s2, 0x7ff
	s_mov_b64 s[36:37], 0x80
	v_writelane_b32 v252, s77, 60
	v_writelane_b32 v254, s95, 51
	s_branch .LBB0_103
